# attention loop: diagonal-tile bias blocks moved out of line so the per-tile common path falls through (no taken branch, 4 x 66 fewer lines in the hot loop)
# baseline (speedup 1.0000x reference)
; template <int KS> __device__ __forceinline__ void pv_ks(f32x16* o, int vb, bf16x8 pa) {
;     const s16x4 l0 = tr_read<v_rd_off(0, KS, 0)>(vb), h0 = tr_read<v_rd_off(0, KS, 1)>(vb), l1 = tr_read<v_rd_off(1, KS, 0)>(vb), h1 = tr_read<v_rd_off(1, KS, 1)>(vb);
;     const s16x4 l2 = tr_read<v_rd_off(2, KS, 0)>(vb), h2 = tr_read<v_rd_off(2, KS, 1)>(vb), l3 = tr_read<v_rd_off(3, KS, 0)>(vb), h3 = tr_read<v_rd_off(3, KS, 1)>(vb);
;     ...
;     asm volatile("s_waitcnt lgkmcnt(6)" ::: "memory"); SBAR();
;     o[0] = __builtin_amdgcn_mfma_f32_32x32x16_bf16(pa, PK(l0, h0), o[0], 0, 0, 0);
;     asm volatile("s_waitcnt lgkmcnt(4)" ::: "memory"); SBAR();
;     o[1] = __builtin_amdgcn_mfma_f32_32x32x16_bf16(pa, PK(l1, h1), o[1], 0, 0, 0);
;     asm volatile("s_waitcnt lgkmcnt(2)" ::: "memory"); SBAR();
;     o[2] = __builtin_amdgcn_mfma_f32_32x32x16_bf16(pa, PK(l2, h2), o[2], 0, 0, 0);
;     asm volatile("s_waitcnt lgkmcnt(0)" ::: "memory"); SBAR();
;     o[3] = __builtin_amdgcn_mfma_f32_32x32x16_bf16(pa, PK(l3, h3), o[3], 0, 0, 0);
;     ...
; }
; __device__ __forceinline__ void pv_d0(f32x16* o, int vb, bf16x8 pa0, bf16x8 pa1, bf16x8 pa2, bf16x8 pa3) {
;     __builtin_amdgcn_s_setprio(1);
;     pv_ks<0>(o, vb, pa0); pv_ks<1>(o, vb, pa1); pv_ks<2>(o, vb, pa2); pv_ks<3>(o, vb, pa3);
;     __builtin_amdgcn_s_setprio(0);
; }
; __device__ __forceinline__ void exp_half(f32x16& p) {
; #pragma unroll
;     for (int r = 0; r < 16; ++r) p[r] = __builtin_amdgcn_exp2f(p[r]);
; }
; __device__ __forceinline__ void pack_p(const f32x16& p0, const f32x16& p1, float& l_reg, bf16x8& pa0, bf16x8& pa1, bf16x8& pa2, bf16x8& pa3) {
;     float ps = 0;
; #pragma unroll
;     for (int r = 0; r < 16; ++r) ps += p0[r];
; #pragma unroll
;     for (int r = 0; r < 16; ++r) ps += p1[r];
;     l_reg += ps;
;     ...
;     PK4(p0, 0, pa0); PK4(p0, 8, pa1); PK4(p1, 0, pa2); PK4(p1, 8, pa3);
;     ...
; }
; template <int ND0> __device__ __forceinline__ void qkt(f32x16& p0, f32x16& p1, const char* Ks, const bf16x8* qr, int r32, int hi, int colB0) {
; #pragma unroll
;     for (int d0 = 0; d0 < ND0; ++d0) { const int cb = colB0 + (d0 * 16 + hi * 8) * 2;
;         const bf16x8 b0 = *reinterpret_cast<const bf16x8*>(Ks + KSWZ(r32, cb));
;         const bf16x8 b1 = *reinterpret_cast<const bf16x8*>(Ks + KSWZ(32 + r32, cb));
;         p0 = __builtin_amdgcn_mfma_f32_32x32x16_bf16(b0, qr[d0], p0, 0, 0, 0);
.Lsym_nostage_s0:
	s_waitcnt lgkmcnt(14)
	v_mfma_f32_32x32x16_bf16 v[48:63], v[128:131], v[144:147], v[48:63]
	ds_read_b64_tr_b16 v[144:145], v252 offset:4096
	ds_read_b64_tr_b16 v[146:147], v252 offset:6144
	v_exp_f32_e32 v88, v88
	v_exp_f32_e32 v89, v89
	v_exp_f32_e32 v90, v90
	s_waitcnt lgkmcnt(14)
	v_mfma_f32_32x32x16_bf16 v[32:47], v[128:131], v[148:151], v[32:47]
	ds_read_b64_tr_b16 v[148:149], v252 offset:4608
	ds_read_b64_tr_b16 v[150:151], v252 offset:6656
	v_exp_f32_e32 v91, v91
	v_add_f32_e32 v182, v88, v182
	v_add_f32_e32 v182, v89, v182
	v_cvt_pk_bf16_f32 v132, v88, v89
	v_exp_f32_e32 v92, v92
	s_waitcnt lgkmcnt(11)
	v_mfma_f32_32x32x16_bf16 v[112:127], v[192:195], v[172:175], v[112:127]
	v_exp_f32_e32 v93, v93
	v_add_f32_e32 v182, v90, v182
	v_add_f32_e32 v182, v91, v182
	v_cvt_pk_bf16_f32 v133, v90, v91
	v_mfma_f32_32x32x16_bf16 v[16:31], v[128:131], v[152:155], v[16:31]
	ds_read_b64_tr_b16 v[152:153], v252 offset:5120
	ds_read_b64_tr_b16 v[154:155], v252 offset:7168
	v_exp_f32_e32 v94, v94
	v_exp_f32_e32 v95, v95
	v_add_f32_e32 v182, v92, v182
	v_add_f32_e32 v182, v93, v182
	s_waitcnt lgkmcnt(12)
	v_mfma_f32_32x32x16_bf16 v[96:111], v[196:199], v[172:175], v[96:111]
	v_cvt_pk_bf16_f32 v134, v92, v93
	v_cvt_pk_bf16_f32 v135, v94, v95
	v_add_f32_e32 v182, v94, v182
	v_add_f32_e32 v182, v95, v182
	v_exp_f32_e32 v64, v64
	v_mfma_f32_32x32x16_bf16 v[0:15], v[128:131], v[156:159], v[0:15]
	ds_read_b64_tr_b16 v[156:157], v252 offset:5632
	ds_read_b64_tr_b16 v[158:159], v252 offset:7680
	v_exp_f32_e32 v65, v65
	v_exp_f32_e32 v66, v66
	v_exp_f32_e32 v67, v67
	v_add_f32_e32 v182, v64, v182
	s_waitcnt lgkmcnt(13)
	v_mfma_f32_32x32x16_bf16 v[112:127], v[200:203], v[168:171], v[112:127]
	v_add_f32_e32 v182, v65, v182
	v_cvt_pk_bf16_f32 v136, v64, v65
	v_exp_f32_e32 v68, v68
	v_exp_f32_e32 v69, v69
	s_waitcnt lgkmcnt(6)
	v_mfma_f32_32x32x16_bf16 v[48:63], v[132:135], v[144:147], v[48:63]
	ds_read_b64_tr_b16 v[144:145], v252 offset:8192
	ds_read_b64_tr_b16 v[146:147], v252 offset:10240
	v_add_f32_e32 v182, v66, v182
	v_add_f32_e32 v182, v67, v182
	v_cvt_pk_bf16_f32 v137, v66, v67
	v_exp_f32_e32 v70, v70
	v_mfma_f32_32x32x16_bf16 v[96:111], v[204:207], v[168:171], v[96:111]
	v_exp_f32_e32 v71, v71
	v_add_f32_e32 v182, v68, v182
	v_add_f32_e32 v182, v69, v182
	v_cvt_pk_bf16_f32 v138, v68, v69
	v_cvt_pk_bf16_f32 v139, v70, v71
	v_add_f32_e32 v182, v70, v182
	s_waitcnt lgkmcnt(6)
	v_mfma_f32_32x32x16_bf16 v[32:47], v[132:135], v[148:151], v[32:47]
	ds_read_b64_tr_b16 v[148:149], v252 offset:8704
	ds_read_b64_tr_b16 v[150:151], v252 offset:10752
	v_add_f32_e32 v182, v71, v182
	v_exp_f32_e32 v72, v72
	v_exp_f32_e32 v73, v73
	v_exp_f32_e32 v74, v74
	v_mfma_f32_32x32x16_bf16 v[112:127], v[208:211], v[164:167], v[112:127]
	v_exp_f32_e32 v75, v75
	v_add_f32_e32 v182, v72, v182
	v_add_f32_e32 v182, v73, v182
	v_cvt_pk_bf16_f32 v140, v72, v73
	s_waitcnt lgkmcnt(6)
	v_mfma_f32_32x32x16_bf16 v[16:31], v[132:135], v[152:155], v[16:31]
	ds_read_b64_tr_b16 v[152:153], v252 offset:9216
	ds_read_b64_tr_b16 v[154:155], v252 offset:11264
	v_exp_f32_e32 v76, v76
	v_exp_f32_e32 v77, v77
	v_add_f32_e32 v182, v74, v182
	v_add_f32_e32 v182, v75, v182
	v_mfma_f32_32x32x16_bf16 v[96:111], v[212:215], v[164:167], v[96:111]
	v_cvt_pk_bf16_f32 v141, v74, v75
	v_exp_f32_e32 v78, v78
	v_exp_f32_e32 v79, v79
	v_add_f32_e32 v182, v76, v182
	s_waitcnt lgkmcnt(6)
; template <int KS> __device__ __forceinline__ void pv_ks(f32x16* o, int vb, bf16x8 pa) {
;     const s16x4 l0 = tr_read<v_rd_off(0, KS, 0)>(vb), h0 = tr_read<v_rd_off(0, KS, 1)>(vb), l1 = tr_read<v_rd_off(1, KS, 0)>(vb), h1 = tr_read<v_rd_off(1, KS, 1)>(vb);
;     const s16x4 l2 = tr_read<v_rd_off(2, KS, 0)>(vb), h2 = tr_read<v_rd_off(2, KS, 1)>(vb), l3 = tr_read<v_rd_off(3, KS, 0)>(vb), h3 = tr_read<v_rd_off(3, KS, 1)>(vb);
;     ...
;     asm volatile("s_waitcnt lgkmcnt(6)" ::: "memory"); SBAR();
;     o[0] = __builtin_amdgcn_mfma_f32_32x32x16_bf16(pa, PK(l0, h0), o[0], 0, 0, 0);
;     asm volatile("s_waitcnt lgkmcnt(4)" ::: "memory"); SBAR();
;     o[1] = __builtin_amdgcn_mfma_f32_32x32x16_bf16(pa, PK(l1, h1), o[1], 0, 0, 0);
;     asm volatile("s_waitcnt lgkmcnt(2)" ::: "memory"); SBAR();
;     o[2] = __builtin_amdgcn_mfma_f32_32x32x16_bf16(pa, PK(l2, h2), o[2], 0, 0, 0);
;     asm volatile("s_waitcnt lgkmcnt(0)" ::: "memory"); SBAR();
;     o[3] = __builtin_amdgcn_mfma_f32_32x32x16_bf16(pa, PK(l3, h3), o[3], 0, 0, 0);
;     ...
; }
; __device__ __forceinline__ void pv_d0(f32x16* o, int vb, bf16x8 pa0, bf16x8 pa1, bf16x8 pa2, bf16x8 pa3) {
;     __builtin_amdgcn_s_setprio(1);
;     pv_ks<0>(o, vb, pa0); pv_ks<1>(o, vb, pa1); pv_ks<2>(o, vb, pa2); pv_ks<3>(o, vb, pa3);
;     __builtin_amdgcn_s_setprio(0);
; }
; __device__ __forceinline__ void exp_half(f32x16& p) {
; #pragma unroll
;     for (int r = 0; r < 16; ++r) p[r] = __builtin_amdgcn_exp2f(p[r]);
; }
; __device__ __forceinline__ void pack_p(const f32x16& p0, const f32x16& p1, float& l_reg, bf16x8& pa0, bf16x8& pa1, bf16x8& pa2, bf16x8& pa3) {
;     float ps = 0;
; #pragma unroll
;     for (int r = 0; r < 16; ++r) ps += p0[r];
; #pragma unroll
;     for (int r = 0; r < 16; ++r) ps += p1[r];
;     l_reg += ps;
;     ...
;     PK4(p0, 0, pa0); PK4(p0, 8, pa1); PK4(p1, 0, pa2); PK4(p1, 8, pa3);
;     ...
; }
; template <int ND0> __device__ __forceinline__ void qkt(f32x16& p0, f32x16& p1, const char* Ks, const bf16x8* qr, int r32, int hi, int colB0) {
; #pragma unroll
;     for (int d0 = 0; d0 < ND0; ++d0) { const int cb = colB0 + (d0 * 16 + hi * 8) * 2;
;         const bf16x8 b0 = *reinterpret_cast<const bf16x8*>(Ks + KSWZ(r32, cb));
;         const bf16x8 b1 = *reinterpret_cast<const bf16x8*>(Ks + KSWZ(32 + r32, cb));
;         p0 = __builtin_amdgcn_mfma_f32_32x32x16_bf16(b0, qr[d0], p0, 0, 0, 0);
	v_mfma_f32_32x32x16_bf16 v[0:15], v[132:135], v[156:159], v[0:15]
	ds_read_b64_tr_b16 v[156:157], v252 offset:9728
	ds_read_b64_tr_b16 v[158:159], v252 offset:11776
	v_add_f32_e32 v182, v77, v182
	v_cvt_pk_bf16_f32 v142, v76, v77
	v_cvt_pk_bf16_f32 v143, v78, v79
	v_add_f32_e32 v182, v78, v182
	v_add_f32_e32 v182, v79, v182
	s_cmp_lt_i32 s55, 0
	s_cselect_b32 s100, -1.0, 1.0
	v_mul_f32_e32 v185, s100, v186
	v_mfma_f32_32x32x16_bf16 v[112:127], v[216:219], v[160:163], v[112:127]
	v_fma_f32 v187, -v185, v183, s16
	v_fmamk_f32 v80, v185, 0x00000000, v187
	v_fmamk_f32 v81, v185, 0x3f800000, v187
	v_fmamk_f32 v82, v185, 0x40000000, v187
	v_fmamk_f32 v83, v185, 0x40400000, v187
	v_fmamk_f32 v84, v185, 0x41000000, v187
	v_mfma_f32_32x32x16_bf16 v[96:111], v[220:223], v[160:163], v[96:111]
	v_fmamk_f32 v85, v185, 0x41100000, v187
	v_fmamk_f32 v86, v185, 0x41200000, v187
	v_fmamk_f32 v87, v185, 0x41300000, v187
	v_fmamk_f32 v88, v185, 0x41800000, v187
	v_fmamk_f32 v89, v185, 0x41880000, v187
	v_fmamk_f32 v90, v185, 0x41900000, v187
	s_waitcnt lgkmcnt(6)
	v_mfma_f32_32x32x16_bf16 v[48:63], v[136:139], v[144:147], v[48:63]
	ds_read_b64_tr_b16 v[144:145], v252 offset:12288
	ds_read_b64_tr_b16 v[146:147], v252 offset:14336
	v_fmamk_f32 v91, v185, 0x41980000, v187
	v_fmamk_f32 v92, v185, 0x41c00000, v187
	v_fmamk_f32 v93, v185, 0x41c80000, v187
	v_fmamk_f32 v94, v185, 0x41d00000, v187
	v_fmamk_f32 v95, v185, 0x41d80000, v187
	v_fmamk_f32 v64, v185, 0x42000000, v187
	s_waitcnt lgkmcnt(6)
	v_mfma_f32_32x32x16_bf16 v[32:47], v[136:139], v[148:151], v[32:47]
	ds_read_b64_tr_b16 v[148:149], v252 offset:12800
	ds_read_b64_tr_b16 v[150:151], v252 offset:14848
	v_fmamk_f32 v65, v185, 0x42040000, v187
	v_fmamk_f32 v66, v185, 0x42080000, v187
	v_fmamk_f32 v67, v185, 0x420c0000, v187
	v_fmamk_f32 v68, v185, 0x42200000, v187
	v_fmamk_f32 v69, v185, 0x42240000, v187
	v_fmamk_f32 v70, v185, 0x42280000, v187
	s_waitcnt lgkmcnt(6)
	v_mfma_f32_32x32x16_bf16 v[16:31], v[136:139], v[152:155], v[16:31]
	ds_read_b64_tr_b16 v[152:153], v252 offset:13312
	ds_read_b64_tr_b16 v[154:155], v252 offset:15360
	v_fmamk_f32 v71, v185, 0x422c0000, v187
	v_fmamk_f32 v72, v185, 0x42400000, v187
	v_fmamk_f32 v73, v185, 0x42440000, v187
	v_fmamk_f32 v74, v185, 0x42480000, v187
	v_fmamk_f32 v75, v185, 0x424c0000, v187
	v_fmamk_f32 v76, v185, 0x42600000, v187
	s_waitcnt lgkmcnt(6)
	v_mfma_f32_32x32x16_bf16 v[0:15], v[136:139], v[156:159], v[0:15]
	ds_read_b64_tr_b16 v[156:157], v252 offset:13824
	ds_read_b64_tr_b16 v[158:159], v252 offset:15872
	v_fmamk_f32 v77, v185, 0x42640000, v187
	v_fmamk_f32 v78, v185, 0x42680000, v187
	v_fmamk_f32 v79, v185, 0x426c0000, v187
	v_exp_f32_e32 v112, v112
	v_exp_f32_e32 v113, v113
	s_waitcnt lgkmcnt(6)
	v_mfma_f32_32x32x16_bf16 v[48:63], v[140:143], v[144:147], v[48:63]
	ds_read_b64_tr_b16 v[144:145], v252 offset:16384
	ds_read_b64_tr_b16 v[146:147], v252 offset:18432
	v_exp_f32_e32 v114, v114
	v_exp_f32_e32 v115, v115
	v_add_f32_e32 v182, v112, v182
	v_add_f32_e32 v182, v113, v182
	s_waitcnt lgkmcnt(6)
	v_mfma_f32_32x32x16_bf16 v[32:47], v[140:143], v[148:151], v[32:47]
	ds_read_b64_tr_b16 v[148:149], v252 offset:16896
	ds_read_b64_tr_b16 v[150:151], v252 offset:18944
	v_cvt_pk_bf16_f32 v128, v112, v113
	v_exp_f32_e32 v116, v116
	v_exp_f32_e32 v117, v117
	v_add_f32_e32 v182, v114, v182
	s_waitcnt lgkmcnt(6)
	v_mfma_f32_32x32x16_bf16 v[16:31], v[140:143], v[152:155], v[16:31]
	ds_read_b64_tr_b16 v[152:153], v252 offset:17408
	ds_read_b64_tr_b16 v[154:155], v252 offset:19456
	v_add_f32_e32 v182, v115, v182
	v_cvt_pk_bf16_f32 v129, v114, v115
	v_exp_f32_e32 v118, v118
	v_exp_f32_e32 v119, v119
	s_waitcnt lgkmcnt(6)
	v_mfma_f32_32x32x16_bf16 v[0:15], v[140:143], v[156:159], v[0:15]
	ds_read_b64_tr_b16 v[156:157], v252 offset:17920
	ds_read_b64_tr_b16 v[158:159], v252 offset:19968
	v_add_f32_e32 v182, v116, v182
	v_add_f32_e32 v182, v117, v182
	v_cvt_pk_bf16_f32 v130, v116, v117
	v_cvt_pk_bf16_f32 v131, v118, v119
	v_add_f32_e32 v182, v118, v182
	v_add_f32_e32 v182, v119, v182
	s_add_i32 s100, s55, 62
	s_cmp_lt_u32 s100, 93
	s_cbranch_scc1 .Lsym_diagblk_s0

; template <int KS> __device__ __forceinline__ void pv_ks(f32x16* o, int vb, bf16x8 pa) {
;     const s16x4 l0 = tr_read<v_rd_off(0, KS, 0)>(vb), h0 = tr_read<v_rd_off(0, KS, 1)>(vb), l1 = tr_read<v_rd_off(1, KS, 0)>(vb), h1 = tr_read<v_rd_off(1, KS, 1)>(vb);
;     const s16x4 l2 = tr_read<v_rd_off(2, KS, 0)>(vb), h2 = tr_read<v_rd_off(2, KS, 1)>(vb), l3 = tr_read<v_rd_off(3, KS, 0)>(vb), h3 = tr_read<v_rd_off(3, KS, 1)>(vb);
;     ...
;     asm volatile("s_waitcnt lgkmcnt(6)" ::: "memory"); SBAR();
;     o[0] = __builtin_amdgcn_mfma_f32_32x32x16_bf16(pa, PK(l0, h0), o[0], 0, 0, 0);
;     asm volatile("s_waitcnt lgkmcnt(4)" ::: "memory"); SBAR();
;     o[1] = __builtin_amdgcn_mfma_f32_32x32x16_bf16(pa, PK(l1, h1), o[1], 0, 0, 0);
;     asm volatile("s_waitcnt lgkmcnt(2)" ::: "memory"); SBAR();
;     o[2] = __builtin_amdgcn_mfma_f32_32x32x16_bf16(pa, PK(l2, h2), o[2], 0, 0, 0);
;     asm volatile("s_waitcnt lgkmcnt(0)" ::: "memory"); SBAR();
;     o[3] = __builtin_amdgcn_mfma_f32_32x32x16_bf16(pa, PK(l3, h3), o[3], 0, 0, 0);
;     ...
; }
; __device__ __forceinline__ void pv_d0(f32x16* o, int vb, bf16x8 pa0, bf16x8 pa1, bf16x8 pa2, bf16x8 pa3) {
;     __builtin_amdgcn_s_setprio(1);
;     pv_ks<0>(o, vb, pa0); pv_ks<1>(o, vb, pa1); pv_ks<2>(o, vb, pa2); pv_ks<3>(o, vb, pa3);
;     __builtin_amdgcn_s_setprio(0);
; }
; __device__ __forceinline__ void exp_half(f32x16& p) {
; #pragma unroll
;     for (int r = 0; r < 16; ++r) p[r] = __builtin_amdgcn_exp2f(p[r]);
; }
; __device__ __forceinline__ void pack_p(const f32x16& p0, const f32x16& p1, float& l_reg, bf16x8& pa0, bf16x8& pa1, bf16x8& pa2, bf16x8& pa3) {
;     float ps = 0;
; #pragma unroll
;     for (int r = 0; r < 16; ++r) ps += p0[r];
; #pragma unroll
;     for (int r = 0; r < 16; ++r) ps += p1[r];
;     l_reg += ps;
;     ...
;     PK4(p0, 0, pa0); PK4(p0, 8, pa1); PK4(p1, 0, pa2); PK4(p1, 8, pa3);
;     ...
; }
; template <int ND0> __device__ __forceinline__ void qkt(f32x16& p0, f32x16& p1, const char* Ks, const bf16x8* qr, int r32, int hi, int colB0) {
; #pragma unroll
;     for (int d0 = 0; d0 < ND0; ++d0) { const int cb = colB0 + (d0 * 16 + hi * 8) * 2;
;         const bf16x8 b0 = *reinterpret_cast<const bf16x8*>(Ks + KSWZ(r32, cb));
;         const bf16x8 b1 = *reinterpret_cast<const bf16x8*>(Ks + KSWZ(32 + r32, cb));
;         p0 = __builtin_amdgcn_mfma_f32_32x32x16_bf16(b0, qr[d0], p0, 0, 0, 0);
.Lsym_nostage_s1:
	s_waitcnt lgkmcnt(14)
	v_mfma_f32_32x32x16_bf16 v[48:63], v[128:131], v[144:147], v[48:63]
	ds_read_b64_tr_b16 v[144:145], v252 offset:20480
	ds_read_b64_tr_b16 v[146:147], v252 offset:22528
	v_exp_f32_e32 v120, v120
	v_exp_f32_e32 v121, v121
	v_exp_f32_e32 v122, v122
	s_waitcnt lgkmcnt(14)
	v_mfma_f32_32x32x16_bf16 v[32:47], v[128:131], v[148:151], v[32:47]
	ds_read_b64_tr_b16 v[148:149], v252 offset:20992
	ds_read_b64_tr_b16 v[150:151], v252 offset:23040
	v_exp_f32_e32 v123, v123
	v_add_f32_e32 v182, v120, v182
	v_add_f32_e32 v182, v121, v182
	v_cvt_pk_bf16_f32 v132, v120, v121
	v_exp_f32_e32 v124, v124
	s_waitcnt lgkmcnt(11)
	v_mfma_f32_32x32x16_bf16 v[80:95], v[192:195], v[172:175], v[80:95]
	v_exp_f32_e32 v125, v125
	v_add_f32_e32 v182, v122, v182
	v_add_f32_e32 v182, v123, v182
	v_cvt_pk_bf16_f32 v133, v122, v123
	v_mfma_f32_32x32x16_bf16 v[16:31], v[128:131], v[152:155], v[16:31]
	ds_read_b64_tr_b16 v[152:153], v252 offset:21504
	ds_read_b64_tr_b16 v[154:155], v252 offset:23552
	v_exp_f32_e32 v126, v126
	v_exp_f32_e32 v127, v127
	v_add_f32_e32 v182, v124, v182
	v_add_f32_e32 v182, v125, v182
	s_waitcnt lgkmcnt(12)
	v_mfma_f32_32x32x16_bf16 v[64:79], v[196:199], v[172:175], v[64:79]
	v_cvt_pk_bf16_f32 v134, v124, v125
	v_cvt_pk_bf16_f32 v135, v126, v127
	v_add_f32_e32 v182, v126, v182
	v_add_f32_e32 v182, v127, v182
	v_exp_f32_e32 v96, v96
	v_mfma_f32_32x32x16_bf16 v[0:15], v[128:131], v[156:159], v[0:15]
	ds_read_b64_tr_b16 v[156:157], v252 offset:22016
	ds_read_b64_tr_b16 v[158:159], v252 offset:24064
	v_exp_f32_e32 v97, v97
	v_exp_f32_e32 v98, v98
	v_exp_f32_e32 v99, v99
	v_add_f32_e32 v182, v96, v182
	s_waitcnt lgkmcnt(13)
	v_mfma_f32_32x32x16_bf16 v[80:95], v[200:203], v[168:171], v[80:95]
	v_add_f32_e32 v182, v97, v182
	v_cvt_pk_bf16_f32 v136, v96, v97
	v_exp_f32_e32 v100, v100
	v_exp_f32_e32 v101, v101
	s_waitcnt lgkmcnt(6)
	v_mfma_f32_32x32x16_bf16 v[48:63], v[132:135], v[144:147], v[48:63]
	ds_read_b64_tr_b16 v[144:145], v252 offset:24576
	ds_read_b64_tr_b16 v[146:147], v252 offset:26624
	v_add_f32_e32 v182, v98, v182
	v_add_f32_e32 v182, v99, v182
	v_cvt_pk_bf16_f32 v137, v98, v99
	v_exp_f32_e32 v102, v102
	v_mfma_f32_32x32x16_bf16 v[64:79], v[204:207], v[168:171], v[64:79]
	v_exp_f32_e32 v103, v103
	v_add_f32_e32 v182, v100, v182
	v_add_f32_e32 v182, v101, v182
	v_cvt_pk_bf16_f32 v138, v100, v101
	v_cvt_pk_bf16_f32 v139, v102, v103
	v_add_f32_e32 v182, v102, v182
	s_waitcnt lgkmcnt(6)
	v_mfma_f32_32x32x16_bf16 v[32:47], v[132:135], v[148:151], v[32:47]
	ds_read_b64_tr_b16 v[148:149], v252 offset:25088
	ds_read_b64_tr_b16 v[150:151], v252 offset:27136
	v_add_f32_e32 v182, v103, v182
	v_exp_f32_e32 v104, v104
	v_exp_f32_e32 v105, v105
	v_exp_f32_e32 v106, v106
	v_mfma_f32_32x32x16_bf16 v[80:95], v[208:211], v[164:167], v[80:95]
	v_exp_f32_e32 v107, v107
	v_add_f32_e32 v182, v104, v182
	v_add_f32_e32 v182, v105, v182
	v_cvt_pk_bf16_f32 v140, v104, v105
	s_waitcnt lgkmcnt(6)
	v_mfma_f32_32x32x16_bf16 v[16:31], v[132:135], v[152:155], v[16:31]
	ds_read_b64_tr_b16 v[152:153], v252 offset:25600
	ds_read_b64_tr_b16 v[154:155], v252 offset:27648
	v_exp_f32_e32 v108, v108
	v_exp_f32_e32 v109, v109
	v_add_f32_e32 v182, v106, v182
	v_add_f32_e32 v182, v107, v182
	v_mfma_f32_32x32x16_bf16 v[64:79], v[212:215], v[164:167], v[64:79]
	v_cvt_pk_bf16_f32 v141, v106, v107
	v_exp_f32_e32 v110, v110
	v_exp_f32_e32 v111, v111
	v_add_f32_e32 v182, v108, v182
	s_waitcnt lgkmcnt(6)
; template <int KS> __device__ __forceinline__ void pv_ks(f32x16* o, int vb, bf16x8 pa) {
;     const s16x4 l0 = tr_read<v_rd_off(0, KS, 0)>(vb), h0 = tr_read<v_rd_off(0, KS, 1)>(vb), l1 = tr_read<v_rd_off(1, KS, 0)>(vb), h1 = tr_read<v_rd_off(1, KS, 1)>(vb);
;     const s16x4 l2 = tr_read<v_rd_off(2, KS, 0)>(vb), h2 = tr_read<v_rd_off(2, KS, 1)>(vb), l3 = tr_read<v_rd_off(3, KS, 0)>(vb), h3 = tr_read<v_rd_off(3, KS, 1)>(vb);
;     ...
;     asm volatile("s_waitcnt lgkmcnt(6)" ::: "memory"); SBAR();
;     o[0] = __builtin_amdgcn_mfma_f32_32x32x16_bf16(pa, PK(l0, h0), o[0], 0, 0, 0);
;     asm volatile("s_waitcnt lgkmcnt(4)" ::: "memory"); SBAR();
;     o[1] = __builtin_amdgcn_mfma_f32_32x32x16_bf16(pa, PK(l1, h1), o[1], 0, 0, 0);
;     asm volatile("s_waitcnt lgkmcnt(2)" ::: "memory"); SBAR();
;     o[2] = __builtin_amdgcn_mfma_f32_32x32x16_bf16(pa, PK(l2, h2), o[2], 0, 0, 0);
;     asm volatile("s_waitcnt lgkmcnt(0)" ::: "memory"); SBAR();
;     o[3] = __builtin_amdgcn_mfma_f32_32x32x16_bf16(pa, PK(l3, h3), o[3], 0, 0, 0);
;     ...
; }
; __device__ __forceinline__ void pv_d0(f32x16* o, int vb, bf16x8 pa0, bf16x8 pa1, bf16x8 pa2, bf16x8 pa3) {
;     __builtin_amdgcn_s_setprio(1);
;     pv_ks<0>(o, vb, pa0); pv_ks<1>(o, vb, pa1); pv_ks<2>(o, vb, pa2); pv_ks<3>(o, vb, pa3);
;     __builtin_amdgcn_s_setprio(0);
; }
; __device__ __forceinline__ void exp_half(f32x16& p) {
; #pragma unroll
;     for (int r = 0; r < 16; ++r) p[r] = __builtin_amdgcn_exp2f(p[r]);
; }
; __device__ __forceinline__ void pack_p(const f32x16& p0, const f32x16& p1, float& l_reg, bf16x8& pa0, bf16x8& pa1, bf16x8& pa2, bf16x8& pa3) {
;     float ps = 0;
; #pragma unroll
;     for (int r = 0; r < 16; ++r) ps += p0[r];
; #pragma unroll
;     for (int r = 0; r < 16; ++r) ps += p1[r];
;     l_reg += ps;
;     ...
;     PK4(p0, 0, pa0); PK4(p0, 8, pa1); PK4(p1, 0, pa2); PK4(p1, 8, pa3);
;     ...
; }
; template <int ND0> __device__ __forceinline__ void qkt(f32x16& p0, f32x16& p1, const char* Ks, const bf16x8* qr, int r32, int hi, int colB0) {
; #pragma unroll
;     for (int d0 = 0; d0 < ND0; ++d0) { const int cb = colB0 + (d0 * 16 + hi * 8) * 2;
;         const bf16x8 b0 = *reinterpret_cast<const bf16x8*>(Ks + KSWZ(r32, cb));
;         const bf16x8 b1 = *reinterpret_cast<const bf16x8*>(Ks + KSWZ(32 + r32, cb));
;         p0 = __builtin_amdgcn_mfma_f32_32x32x16_bf16(b0, qr[d0], p0, 0, 0, 0);
	v_mfma_f32_32x32x16_bf16 v[0:15], v[132:135], v[156:159], v[0:15]
	ds_read_b64_tr_b16 v[156:157], v252 offset:26112
	ds_read_b64_tr_b16 v[158:159], v252 offset:28160
	v_add_f32_e32 v182, v109, v182
	v_cvt_pk_bf16_f32 v142, v108, v109
	v_cvt_pk_bf16_f32 v143, v110, v111
	v_add_f32_e32 v182, v110, v182
	v_add_f32_e32 v182, v111, v182
	s_cmp_lt_i32 s55, 0
	s_cselect_b32 s100, -1.0, 1.0
	v_mul_f32_e32 v185, s100, v186
	v_mfma_f32_32x32x16_bf16 v[80:95], v[216:219], v[160:163], v[80:95]
	v_fma_f32 v187, -v185, v183, s16
	v_fmamk_f32 v112, v185, 0x00000000, v187
	v_fmamk_f32 v113, v185, 0x3f800000, v187
	v_fmamk_f32 v114, v185, 0x40000000, v187
	v_fmamk_f32 v115, v185, 0x40400000, v187
	v_fmamk_f32 v116, v185, 0x41000000, v187
	v_mfma_f32_32x32x16_bf16 v[64:79], v[220:223], v[160:163], v[64:79]
	v_fmamk_f32 v117, v185, 0x41100000, v187
	v_fmamk_f32 v118, v185, 0x41200000, v187
	v_fmamk_f32 v119, v185, 0x41300000, v187
	v_fmamk_f32 v120, v185, 0x41800000, v187
	v_fmamk_f32 v121, v185, 0x41880000, v187
	v_fmamk_f32 v122, v185, 0x41900000, v187
	s_waitcnt lgkmcnt(6)
	v_mfma_f32_32x32x16_bf16 v[48:63], v[136:139], v[144:147], v[48:63]
	ds_read_b64_tr_b16 v[144:145], v252 offset:28672
	ds_read_b64_tr_b16 v[146:147], v252 offset:30720
	v_fmamk_f32 v123, v185, 0x41980000, v187
	v_fmamk_f32 v124, v185, 0x41c00000, v187
	v_fmamk_f32 v125, v185, 0x41c80000, v187
	v_fmamk_f32 v126, v185, 0x41d00000, v187
	v_fmamk_f32 v127, v185, 0x41d80000, v187
	v_fmamk_f32 v96, v185, 0x42000000, v187
	s_waitcnt lgkmcnt(6)
	v_mfma_f32_32x32x16_bf16 v[32:47], v[136:139], v[148:151], v[32:47]
	ds_read_b64_tr_b16 v[148:149], v252 offset:29184
	ds_read_b64_tr_b16 v[150:151], v252 offset:31232
	v_fmamk_f32 v97, v185, 0x42040000, v187
	v_fmamk_f32 v98, v185, 0x42080000, v187
	v_fmamk_f32 v99, v185, 0x420c0000, v187
	v_fmamk_f32 v100, v185, 0x42200000, v187
	v_fmamk_f32 v101, v185, 0x42240000, v187
	v_fmamk_f32 v102, v185, 0x42280000, v187
	s_waitcnt lgkmcnt(6)
	v_mfma_f32_32x32x16_bf16 v[16:31], v[136:139], v[152:155], v[16:31]
	ds_read_b64_tr_b16 v[152:153], v252 offset:29696
	ds_read_b64_tr_b16 v[154:155], v252 offset:31744
	v_fmamk_f32 v103, v185, 0x422c0000, v187
	v_fmamk_f32 v104, v185, 0x42400000, v187
	v_fmamk_f32 v105, v185, 0x42440000, v187
	v_fmamk_f32 v106, v185, 0x42480000, v187
	v_fmamk_f32 v107, v185, 0x424c0000, v187
	v_fmamk_f32 v108, v185, 0x42600000, v187
	s_waitcnt lgkmcnt(6)
	v_mfma_f32_32x32x16_bf16 v[0:15], v[136:139], v[156:159], v[0:15]
	ds_read_b64_tr_b16 v[156:157], v252 offset:30208
	ds_read_b64_tr_b16 v[158:159], v252 offset:32256
	v_fmamk_f32 v109, v185, 0x42640000, v187
	v_fmamk_f32 v110, v185, 0x42680000, v187
	v_fmamk_f32 v111, v185, 0x426c0000, v187
	v_exp_f32_e32 v80, v80
	v_exp_f32_e32 v81, v81
	s_waitcnt lgkmcnt(6)
	v_mfma_f32_32x32x16_bf16 v[48:63], v[140:143], v[144:147], v[48:63]
	ds_read_b64_tr_b16 v[144:145], v252 offset:32768
	ds_read_b64_tr_b16 v[146:147], v252 offset:34816
	v_exp_f32_e32 v82, v82
	v_exp_f32_e32 v83, v83
	v_add_f32_e32 v182, v80, v182
	v_add_f32_e32 v182, v81, v182
	s_waitcnt lgkmcnt(6)
	v_mfma_f32_32x32x16_bf16 v[32:47], v[140:143], v[148:151], v[32:47]
	ds_read_b64_tr_b16 v[148:149], v252 offset:33280
	ds_read_b64_tr_b16 v[150:151], v252 offset:35328
	v_cvt_pk_bf16_f32 v128, v80, v81
	v_exp_f32_e32 v84, v84
	v_exp_f32_e32 v85, v85
	v_add_f32_e32 v182, v82, v182
	s_waitcnt lgkmcnt(6)
	v_mfma_f32_32x32x16_bf16 v[16:31], v[140:143], v[152:155], v[16:31]
	ds_read_b64_tr_b16 v[152:153], v252 offset:33792
	ds_read_b64_tr_b16 v[154:155], v252 offset:35840
	v_add_f32_e32 v182, v83, v182
	v_cvt_pk_bf16_f32 v129, v82, v83
	v_exp_f32_e32 v86, v86
	v_exp_f32_e32 v87, v87
	s_waitcnt lgkmcnt(6)
	v_mfma_f32_32x32x16_bf16 v[0:15], v[140:143], v[156:159], v[0:15]
	ds_read_b64_tr_b16 v[156:157], v252 offset:34304
	ds_read_b64_tr_b16 v[158:159], v252 offset:36352
	v_add_f32_e32 v182, v84, v182
	v_add_f32_e32 v182, v85, v182
	v_cvt_pk_bf16_f32 v130, v84, v85
	v_cvt_pk_bf16_f32 v131, v86, v87
	v_add_f32_e32 v182, v86, v182
	v_add_f32_e32 v182, v87, v182
	s_add_i32 s100, s55, 62
	s_cmp_lt_u32 s100, 93
	s_cbranch_scc1 .Lsym_diagblk_s1

; template <int KS> __device__ __forceinline__ void pv_ks(f32x16* o, int vb, bf16x8 pa) {
;     const s16x4 l0 = tr_read<v_rd_off(0, KS, 0)>(vb), h0 = tr_read<v_rd_off(0, KS, 1)>(vb), l1 = tr_read<v_rd_off(1, KS, 0)>(vb), h1 = tr_read<v_rd_off(1, KS, 1)>(vb);
;     const s16x4 l2 = tr_read<v_rd_off(2, KS, 0)>(vb), h2 = tr_read<v_rd_off(2, KS, 1)>(vb), l3 = tr_read<v_rd_off(3, KS, 0)>(vb), h3 = tr_read<v_rd_off(3, KS, 1)>(vb);
;     ...
;     asm volatile("s_waitcnt lgkmcnt(6)" ::: "memory"); SBAR();
;     o[0] = __builtin_amdgcn_mfma_f32_32x32x16_bf16(pa, PK(l0, h0), o[0], 0, 0, 0);
;     asm volatile("s_waitcnt lgkmcnt(4)" ::: "memory"); SBAR();
;     o[1] = __builtin_amdgcn_mfma_f32_32x32x16_bf16(pa, PK(l1, h1), o[1], 0, 0, 0);
;     asm volatile("s_waitcnt lgkmcnt(2)" ::: "memory"); SBAR();
;     o[2] = __builtin_amdgcn_mfma_f32_32x32x16_bf16(pa, PK(l2, h2), o[2], 0, 0, 0);
;     asm volatile("s_waitcnt lgkmcnt(0)" ::: "memory"); SBAR();
;     o[3] = __builtin_amdgcn_mfma_f32_32x32x16_bf16(pa, PK(l3, h3), o[3], 0, 0, 0);
;     ...
; }
; __device__ __forceinline__ void pv_d0(f32x16* o, int vb, bf16x8 pa0, bf16x8 pa1, bf16x8 pa2, bf16x8 pa3) {
;     __builtin_amdgcn_s_setprio(1);
;     pv_ks<0>(o, vb, pa0); pv_ks<1>(o, vb, pa1); pv_ks<2>(o, vb, pa2); pv_ks<3>(o, vb, pa3);
;     __builtin_amdgcn_s_setprio(0);
; }
; __device__ __forceinline__ void exp_half(f32x16& p) {
; #pragma unroll
;     for (int r = 0; r < 16; ++r) p[r] = __builtin_amdgcn_exp2f(p[r]);
; }
; __device__ __forceinline__ void pack_p(const f32x16& p0, const f32x16& p1, float& l_reg, bf16x8& pa0, bf16x8& pa1, bf16x8& pa2, bf16x8& pa3) {
;     float ps = 0;
; #pragma unroll
;     for (int r = 0; r < 16; ++r) ps += p0[r];
; #pragma unroll
;     for (int r = 0; r < 16; ++r) ps += p1[r];
;     l_reg += ps;
;     ...
;     PK4(p0, 0, pa0); PK4(p0, 8, pa1); PK4(p1, 0, pa2); PK4(p1, 8, pa3);
;     ...
; }
; template <int ND0> __device__ __forceinline__ void qkt(f32x16& p0, f32x16& p1, const char* Ks, const bf16x8* qr, int r32, int hi, int colB0) {
; #pragma unroll
;     for (int d0 = 0; d0 < ND0; ++d0) { const int cb = colB0 + (d0 * 16 + hi * 8) * 2;
;         const bf16x8 b0 = *reinterpret_cast<const bf16x8*>(Ks + KSWZ(r32, cb));
;         const bf16x8 b1 = *reinterpret_cast<const bf16x8*>(Ks + KSWZ(32 + r32, cb));
;         p0 = __builtin_amdgcn_mfma_f32_32x32x16_bf16(b0, qr[d0], p0, 0, 0, 0);
.Lsym_nostage_s2:
	s_waitcnt lgkmcnt(14)
	v_mfma_f32_32x32x16_bf16 v[48:63], v[128:131], v[144:147], v[48:63]
	ds_read_b64_tr_b16 v[144:145], v252 offset:36864
	ds_read_b64_tr_b16 v[146:147], v252 offset:38912
	v_exp_f32_e32 v88, v88
	v_exp_f32_e32 v89, v89
	v_exp_f32_e32 v90, v90
	s_waitcnt lgkmcnt(14)
	v_mfma_f32_32x32x16_bf16 v[32:47], v[128:131], v[148:151], v[32:47]
	ds_read_b64_tr_b16 v[148:149], v252 offset:37376
	ds_read_b64_tr_b16 v[150:151], v252 offset:39424
	v_exp_f32_e32 v91, v91
	v_add_f32_e32 v182, v88, v182
	v_add_f32_e32 v182, v89, v182
	v_cvt_pk_bf16_f32 v132, v88, v89
	v_exp_f32_e32 v92, v92
	s_waitcnt lgkmcnt(11)
	v_mfma_f32_32x32x16_bf16 v[112:127], v[192:195], v[172:175], v[112:127]
	v_exp_f32_e32 v93, v93
	v_add_f32_e32 v182, v90, v182
	v_add_f32_e32 v182, v91, v182
	v_cvt_pk_bf16_f32 v133, v90, v91
	v_mfma_f32_32x32x16_bf16 v[16:31], v[128:131], v[152:155], v[16:31]
	ds_read_b64_tr_b16 v[152:153], v252 offset:37888
	ds_read_b64_tr_b16 v[154:155], v252 offset:39936
	v_exp_f32_e32 v94, v94
	v_exp_f32_e32 v95, v95
	v_add_f32_e32 v182, v92, v182
	v_add_f32_e32 v182, v93, v182
	s_waitcnt lgkmcnt(12)
	v_mfma_f32_32x32x16_bf16 v[96:111], v[196:199], v[172:175], v[96:111]
	v_cvt_pk_bf16_f32 v134, v92, v93
	v_cvt_pk_bf16_f32 v135, v94, v95
	v_add_f32_e32 v182, v94, v182
	v_add_f32_e32 v182, v95, v182
	v_exp_f32_e32 v64, v64
	v_mfma_f32_32x32x16_bf16 v[0:15], v[128:131], v[156:159], v[0:15]
	ds_read_b64_tr_b16 v[156:157], v252 offset:38400
	ds_read_b64_tr_b16 v[158:159], v252 offset:40448
	v_exp_f32_e32 v65, v65
	v_exp_f32_e32 v66, v66
	v_exp_f32_e32 v67, v67
	v_add_f32_e32 v182, v64, v182
	s_waitcnt lgkmcnt(13)
	v_mfma_f32_32x32x16_bf16 v[112:127], v[200:203], v[168:171], v[112:127]
	v_add_f32_e32 v182, v65, v182
	v_cvt_pk_bf16_f32 v136, v64, v65
	v_exp_f32_e32 v68, v68
	v_exp_f32_e32 v69, v69
	s_waitcnt lgkmcnt(6)
	v_mfma_f32_32x32x16_bf16 v[48:63], v[132:135], v[144:147], v[48:63]
	ds_read_b64_tr_b16 v[144:145], v252 offset:40960
	ds_read_b64_tr_b16 v[146:147], v252 offset:43008
	v_add_f32_e32 v182, v66, v182
	v_add_f32_e32 v182, v67, v182
	v_cvt_pk_bf16_f32 v137, v66, v67
	v_exp_f32_e32 v70, v70
	v_mfma_f32_32x32x16_bf16 v[96:111], v[204:207], v[168:171], v[96:111]
	v_exp_f32_e32 v71, v71
	v_add_f32_e32 v182, v68, v182
	v_add_f32_e32 v182, v69, v182
	v_cvt_pk_bf16_f32 v138, v68, v69
	v_cvt_pk_bf16_f32 v139, v70, v71
	v_add_f32_e32 v182, v70, v182
	s_waitcnt lgkmcnt(6)
	v_mfma_f32_32x32x16_bf16 v[32:47], v[132:135], v[148:151], v[32:47]
	ds_read_b64_tr_b16 v[148:149], v252 offset:41472
	ds_read_b64_tr_b16 v[150:151], v252 offset:43520
	v_add_f32_e32 v182, v71, v182
	v_exp_f32_e32 v72, v72
	v_exp_f32_e32 v73, v73
	v_exp_f32_e32 v74, v74
	v_mfma_f32_32x32x16_bf16 v[112:127], v[208:211], v[164:167], v[112:127]
	v_exp_f32_e32 v75, v75
	v_add_f32_e32 v182, v72, v182
	v_add_f32_e32 v182, v73, v182
	v_cvt_pk_bf16_f32 v140, v72, v73
	s_waitcnt lgkmcnt(6)
	v_mfma_f32_32x32x16_bf16 v[16:31], v[132:135], v[152:155], v[16:31]
	ds_read_b64_tr_b16 v[152:153], v252 offset:41984
	ds_read_b64_tr_b16 v[154:155], v252 offset:44032
	v_exp_f32_e32 v76, v76
	v_exp_f32_e32 v77, v77
	v_add_f32_e32 v182, v74, v182
	v_add_f32_e32 v182, v75, v182
	v_mfma_f32_32x32x16_bf16 v[96:111], v[212:215], v[164:167], v[96:111]
	v_cvt_pk_bf16_f32 v141, v74, v75
	v_exp_f32_e32 v78, v78
	v_exp_f32_e32 v79, v79
	v_add_f32_e32 v182, v76, v182
	s_waitcnt lgkmcnt(6)
; template <int KS> __device__ __forceinline__ void pv_ks(f32x16* o, int vb, bf16x8 pa) {
;     const s16x4 l0 = tr_read<v_rd_off(0, KS, 0)>(vb), h0 = tr_read<v_rd_off(0, KS, 1)>(vb), l1 = tr_read<v_rd_off(1, KS, 0)>(vb), h1 = tr_read<v_rd_off(1, KS, 1)>(vb);
;     const s16x4 l2 = tr_read<v_rd_off(2, KS, 0)>(vb), h2 = tr_read<v_rd_off(2, KS, 1)>(vb), l3 = tr_read<v_rd_off(3, KS, 0)>(vb), h3 = tr_read<v_rd_off(3, KS, 1)>(vb);
;     ...
;     asm volatile("s_waitcnt lgkmcnt(6)" ::: "memory"); SBAR();
;     o[0] = __builtin_amdgcn_mfma_f32_32x32x16_bf16(pa, PK(l0, h0), o[0], 0, 0, 0);
;     asm volatile("s_waitcnt lgkmcnt(4)" ::: "memory"); SBAR();
;     o[1] = __builtin_amdgcn_mfma_f32_32x32x16_bf16(pa, PK(l1, h1), o[1], 0, 0, 0);
;     asm volatile("s_waitcnt lgkmcnt(2)" ::: "memory"); SBAR();
;     o[2] = __builtin_amdgcn_mfma_f32_32x32x16_bf16(pa, PK(l2, h2), o[2], 0, 0, 0);
;     asm volatile("s_waitcnt lgkmcnt(0)" ::: "memory"); SBAR();
;     o[3] = __builtin_amdgcn_mfma_f32_32x32x16_bf16(pa, PK(l3, h3), o[3], 0, 0, 0);
;     ...
; }
; __device__ __forceinline__ void pv_d0(f32x16* o, int vb, bf16x8 pa0, bf16x8 pa1, bf16x8 pa2, bf16x8 pa3) {
;     __builtin_amdgcn_s_setprio(1);
;     pv_ks<0>(o, vb, pa0); pv_ks<1>(o, vb, pa1); pv_ks<2>(o, vb, pa2); pv_ks<3>(o, vb, pa3);
;     __builtin_amdgcn_s_setprio(0);
; }
; __device__ __forceinline__ void exp_half(f32x16& p) {
; #pragma unroll
;     for (int r = 0; r < 16; ++r) p[r] = __builtin_amdgcn_exp2f(p[r]);
; }
; __device__ __forceinline__ void pack_p(const f32x16& p0, const f32x16& p1, float& l_reg, bf16x8& pa0, bf16x8& pa1, bf16x8& pa2, bf16x8& pa3) {
;     float ps = 0;
; #pragma unroll
;     for (int r = 0; r < 16; ++r) ps += p0[r];
; #pragma unroll
;     for (int r = 0; r < 16; ++r) ps += p1[r];
;     l_reg += ps;
;     ...
;     PK4(p0, 0, pa0); PK4(p0, 8, pa1); PK4(p1, 0, pa2); PK4(p1, 8, pa3);
;     ...
; }
; template <int ND0> __device__ __forceinline__ void qkt(f32x16& p0, f32x16& p1, const char* Ks, const bf16x8* qr, int r32, int hi, int colB0) {
; #pragma unroll
;     for (int d0 = 0; d0 < ND0; ++d0) { const int cb = colB0 + (d0 * 16 + hi * 8) * 2;
;         const bf16x8 b0 = *reinterpret_cast<const bf16x8*>(Ks + KSWZ(r32, cb));
;         const bf16x8 b1 = *reinterpret_cast<const bf16x8*>(Ks + KSWZ(32 + r32, cb));
;         p0 = __builtin_amdgcn_mfma_f32_32x32x16_bf16(b0, qr[d0], p0, 0, 0, 0);
	v_mfma_f32_32x32x16_bf16 v[0:15], v[132:135], v[156:159], v[0:15]
	ds_read_b64_tr_b16 v[156:157], v252 offset:42496
	ds_read_b64_tr_b16 v[158:159], v252 offset:44544
	v_add_f32_e32 v182, v77, v182
	v_cvt_pk_bf16_f32 v142, v76, v77
	v_cvt_pk_bf16_f32 v143, v78, v79
	v_add_f32_e32 v182, v78, v182
	v_add_f32_e32 v182, v79, v182
	s_cmp_lt_i32 s55, 0
	s_cselect_b32 s100, -1.0, 1.0
	v_mul_f32_e32 v185, s100, v186
	v_mfma_f32_32x32x16_bf16 v[112:127], v[216:219], v[160:163], v[112:127]
	v_fma_f32 v187, -v185, v183, s16
	v_fmamk_f32 v80, v185, 0x00000000, v187
	v_fmamk_f32 v81, v185, 0x3f800000, v187
	v_fmamk_f32 v82, v185, 0x40000000, v187
	v_fmamk_f32 v83, v185, 0x40400000, v187
	v_fmamk_f32 v84, v185, 0x41000000, v187
	v_mfma_f32_32x32x16_bf16 v[96:111], v[220:223], v[160:163], v[96:111]
	v_fmamk_f32 v85, v185, 0x41100000, v187
	v_fmamk_f32 v86, v185, 0x41200000, v187
	v_fmamk_f32 v87, v185, 0x41300000, v187
	v_fmamk_f32 v88, v185, 0x41800000, v187
	v_fmamk_f32 v89, v185, 0x41880000, v187
	v_fmamk_f32 v90, v185, 0x41900000, v187
	s_waitcnt lgkmcnt(6)
	v_mfma_f32_32x32x16_bf16 v[48:63], v[136:139], v[144:147], v[48:63]
	ds_read_b64_tr_b16 v[144:145], v252 offset:45056
	ds_read_b64_tr_b16 v[146:147], v252 offset:47104
	v_fmamk_f32 v91, v185, 0x41980000, v187
	v_fmamk_f32 v92, v185, 0x41c00000, v187
	v_fmamk_f32 v93, v185, 0x41c80000, v187
	v_fmamk_f32 v94, v185, 0x41d00000, v187
	v_fmamk_f32 v95, v185, 0x41d80000, v187
	v_fmamk_f32 v64, v185, 0x42000000, v187
	s_waitcnt lgkmcnt(6)
	v_mfma_f32_32x32x16_bf16 v[32:47], v[136:139], v[148:151], v[32:47]
	ds_read_b64_tr_b16 v[148:149], v252 offset:45568
	ds_read_b64_tr_b16 v[150:151], v252 offset:47616
	v_fmamk_f32 v65, v185, 0x42040000, v187
	v_fmamk_f32 v66, v185, 0x42080000, v187
	v_fmamk_f32 v67, v185, 0x420c0000, v187
	v_fmamk_f32 v68, v185, 0x42200000, v187
	v_fmamk_f32 v69, v185, 0x42240000, v187
	v_fmamk_f32 v70, v185, 0x42280000, v187
	s_waitcnt lgkmcnt(6)
	v_mfma_f32_32x32x16_bf16 v[16:31], v[136:139], v[152:155], v[16:31]
	ds_read_b64_tr_b16 v[152:153], v252 offset:46080
	ds_read_b64_tr_b16 v[154:155], v252 offset:48128
	v_fmamk_f32 v71, v185, 0x422c0000, v187
	v_fmamk_f32 v72, v185, 0x42400000, v187
	v_fmamk_f32 v73, v185, 0x42440000, v187
	v_fmamk_f32 v74, v185, 0x42480000, v187
	v_fmamk_f32 v75, v185, 0x424c0000, v187
	v_fmamk_f32 v76, v185, 0x42600000, v187
	s_waitcnt lgkmcnt(6)
	v_mfma_f32_32x32x16_bf16 v[0:15], v[136:139], v[156:159], v[0:15]
	ds_read_b64_tr_b16 v[156:157], v252 offset:46592
	ds_read_b64_tr_b16 v[158:159], v252 offset:48640
	v_fmamk_f32 v77, v185, 0x42640000, v187
	v_fmamk_f32 v78, v185, 0x42680000, v187
	v_fmamk_f32 v79, v185, 0x426c0000, v187
	v_exp_f32_e32 v112, v112
	v_exp_f32_e32 v113, v113
	s_waitcnt lgkmcnt(6)
	v_mfma_f32_32x32x16_bf16 v[48:63], v[140:143], v[144:147], v[48:63]
	ds_read_b64_tr_b16 v[144:145], v252 offset:49152
	ds_read_b64_tr_b16 v[146:147], v252 offset:51200
	v_exp_f32_e32 v114, v114
	v_exp_f32_e32 v115, v115
	v_add_f32_e32 v182, v112, v182
	v_add_f32_e32 v182, v113, v182
	s_waitcnt lgkmcnt(6)
	v_mfma_f32_32x32x16_bf16 v[32:47], v[140:143], v[148:151], v[32:47]
	ds_read_b64_tr_b16 v[148:149], v252 offset:49664
	ds_read_b64_tr_b16 v[150:151], v252 offset:51712
	v_cvt_pk_bf16_f32 v128, v112, v113
	v_exp_f32_e32 v116, v116
	v_exp_f32_e32 v117, v117
	v_add_f32_e32 v182, v114, v182
	s_waitcnt lgkmcnt(6)
	v_mfma_f32_32x32x16_bf16 v[16:31], v[140:143], v[152:155], v[16:31]
	ds_read_b64_tr_b16 v[152:153], v252 offset:50176
	ds_read_b64_tr_b16 v[154:155], v252 offset:52224
	v_add_f32_e32 v182, v115, v182
	v_cvt_pk_bf16_f32 v129, v114, v115
	v_exp_f32_e32 v118, v118
	v_exp_f32_e32 v119, v119
	s_waitcnt lgkmcnt(6)
	v_mfma_f32_32x32x16_bf16 v[0:15], v[140:143], v[156:159], v[0:15]
	ds_read_b64_tr_b16 v[156:157], v252 offset:50688
	ds_read_b64_tr_b16 v[158:159], v252 offset:52736
	v_add_f32_e32 v182, v116, v182
	v_add_f32_e32 v182, v117, v182
	v_cvt_pk_bf16_f32 v130, v116, v117
	v_cvt_pk_bf16_f32 v131, v118, v119
	v_add_f32_e32 v182, v118, v182
	v_add_f32_e32 v182, v119, v182
	s_add_i32 s100, s55, 62
	s_cmp_lt_u32 s100, 93
	s_cbranch_scc1 .Lsym_diagblk_s2

; template <int KS> __device__ __forceinline__ void pv_ks(f32x16* o, int vb, bf16x8 pa) {
;     const s16x4 l0 = tr_read<v_rd_off(0, KS, 0)>(vb), h0 = tr_read<v_rd_off(0, KS, 1)>(vb), l1 = tr_read<v_rd_off(1, KS, 0)>(vb), h1 = tr_read<v_rd_off(1, KS, 1)>(vb);
;     const s16x4 l2 = tr_read<v_rd_off(2, KS, 0)>(vb), h2 = tr_read<v_rd_off(2, KS, 1)>(vb), l3 = tr_read<v_rd_off(3, KS, 0)>(vb), h3 = tr_read<v_rd_off(3, KS, 1)>(vb);
;     ...
;     asm volatile("s_waitcnt lgkmcnt(6)" ::: "memory"); SBAR();
;     o[0] = __builtin_amdgcn_mfma_f32_32x32x16_bf16(pa, PK(l0, h0), o[0], 0, 0, 0);
;     asm volatile("s_waitcnt lgkmcnt(4)" ::: "memory"); SBAR();
;     o[1] = __builtin_amdgcn_mfma_f32_32x32x16_bf16(pa, PK(l1, h1), o[1], 0, 0, 0);
;     asm volatile("s_waitcnt lgkmcnt(2)" ::: "memory"); SBAR();
;     o[2] = __builtin_amdgcn_mfma_f32_32x32x16_bf16(pa, PK(l2, h2), o[2], 0, 0, 0);
;     asm volatile("s_waitcnt lgkmcnt(0)" ::: "memory"); SBAR();
;     o[3] = __builtin_amdgcn_mfma_f32_32x32x16_bf16(pa, PK(l3, h3), o[3], 0, 0, 0);
;     ...
; }
; __device__ __forceinline__ void pv_d0(f32x16* o, int vb, bf16x8 pa0, bf16x8 pa1, bf16x8 pa2, bf16x8 pa3) {
;     __builtin_amdgcn_s_setprio(1);
;     pv_ks<0>(o, vb, pa0); pv_ks<1>(o, vb, pa1); pv_ks<2>(o, vb, pa2); pv_ks<3>(o, vb, pa3);
;     __builtin_amdgcn_s_setprio(0);
; }
; __device__ __forceinline__ void exp_half(f32x16& p) {
; #pragma unroll
;     for (int r = 0; r < 16; ++r) p[r] = __builtin_amdgcn_exp2f(p[r]);
; }
; __device__ __forceinline__ void pack_p(const f32x16& p0, const f32x16& p1, float& l_reg, bf16x8& pa0, bf16x8& pa1, bf16x8& pa2, bf16x8& pa3) {
;     float ps = 0;
; #pragma unroll
;     for (int r = 0; r < 16; ++r) ps += p0[r];
; #pragma unroll
;     for (int r = 0; r < 16; ++r) ps += p1[r];
;     l_reg += ps;
;     ...
;     PK4(p0, 0, pa0); PK4(p0, 8, pa1); PK4(p1, 0, pa2); PK4(p1, 8, pa3);
;     ...
; }
; template <int ND0> __device__ __forceinline__ void qkt(f32x16& p0, f32x16& p1, const char* Ks, const bf16x8* qr, int r32, int hi, int colB0) {
; #pragma unroll
;     for (int d0 = 0; d0 < ND0; ++d0) { const int cb = colB0 + (d0 * 16 + hi * 8) * 2;
;         const bf16x8 b0 = *reinterpret_cast<const bf16x8*>(Ks + KSWZ(r32, cb));
;         const bf16x8 b1 = *reinterpret_cast<const bf16x8*>(Ks + KSWZ(32 + r32, cb));
;         p0 = __builtin_amdgcn_mfma_f32_32x32x16_bf16(b0, qr[d0], p0, 0, 0, 0);
.Lsym_nostage_s3:
	s_waitcnt lgkmcnt(14)
	v_mfma_f32_32x32x16_bf16 v[48:63], v[128:131], v[144:147], v[48:63]
	ds_read_b64_tr_b16 v[144:145], v252 offset:53248
	ds_read_b64_tr_b16 v[146:147], v252 offset:55296
	v_exp_f32_e32 v120, v120
	v_exp_f32_e32 v121, v121
	v_exp_f32_e32 v122, v122
	s_waitcnt lgkmcnt(14)
	v_mfma_f32_32x32x16_bf16 v[32:47], v[128:131], v[148:151], v[32:47]
	ds_read_b64_tr_b16 v[148:149], v252 offset:53760
	ds_read_b64_tr_b16 v[150:151], v252 offset:55808
	v_exp_f32_e32 v123, v123
	v_add_f32_e32 v182, v120, v182
	v_add_f32_e32 v182, v121, v182
	v_cvt_pk_bf16_f32 v132, v120, v121
	v_exp_f32_e32 v124, v124
	s_waitcnt lgkmcnt(11)
	v_mfma_f32_32x32x16_bf16 v[80:95], v[192:195], v[172:175], v[80:95]
	v_exp_f32_e32 v125, v125
	v_add_f32_e32 v182, v122, v182
	v_add_f32_e32 v182, v123, v182
	v_cvt_pk_bf16_f32 v133, v122, v123
	v_mfma_f32_32x32x16_bf16 v[16:31], v[128:131], v[152:155], v[16:31]
	ds_read_b64_tr_b16 v[152:153], v252 offset:54272
	ds_read_b64_tr_b16 v[154:155], v252 offset:56320
	v_exp_f32_e32 v126, v126
	v_exp_f32_e32 v127, v127
	v_add_f32_e32 v182, v124, v182
	v_add_f32_e32 v182, v125, v182
	s_waitcnt lgkmcnt(12)
	v_mfma_f32_32x32x16_bf16 v[64:79], v[196:199], v[172:175], v[64:79]
	v_cvt_pk_bf16_f32 v134, v124, v125
	v_cvt_pk_bf16_f32 v135, v126, v127
	v_add_f32_e32 v182, v126, v182
	v_add_f32_e32 v182, v127, v182
	v_exp_f32_e32 v96, v96
	v_mfma_f32_32x32x16_bf16 v[0:15], v[128:131], v[156:159], v[0:15]
	ds_read_b64_tr_b16 v[156:157], v252 offset:54784
	ds_read_b64_tr_b16 v[158:159], v252 offset:56832
	v_exp_f32_e32 v97, v97
	v_exp_f32_e32 v98, v98
	v_exp_f32_e32 v99, v99
	v_add_f32_e32 v182, v96, v182
	s_waitcnt lgkmcnt(13)
	v_mfma_f32_32x32x16_bf16 v[80:95], v[200:203], v[168:171], v[80:95]
	v_add_f32_e32 v182, v97, v182
	v_cvt_pk_bf16_f32 v136, v96, v97
	v_exp_f32_e32 v100, v100
	v_exp_f32_e32 v101, v101
	s_waitcnt lgkmcnt(6)
	v_mfma_f32_32x32x16_bf16 v[48:63], v[132:135], v[144:147], v[48:63]
	ds_read_b64_tr_b16 v[144:145], v252 offset:57344
	ds_read_b64_tr_b16 v[146:147], v252 offset:59392
	v_add_f32_e32 v182, v98, v182
	v_add_f32_e32 v182, v99, v182
	v_cvt_pk_bf16_f32 v137, v98, v99
	v_exp_f32_e32 v102, v102
	v_mfma_f32_32x32x16_bf16 v[64:79], v[204:207], v[168:171], v[64:79]
	v_exp_f32_e32 v103, v103
	v_add_f32_e32 v182, v100, v182
	v_add_f32_e32 v182, v101, v182
	v_cvt_pk_bf16_f32 v138, v100, v101
	v_cvt_pk_bf16_f32 v139, v102, v103
	v_add_f32_e32 v182, v102, v182
	s_waitcnt lgkmcnt(6)
	v_mfma_f32_32x32x16_bf16 v[32:47], v[132:135], v[148:151], v[32:47]
	ds_read_b64_tr_b16 v[148:149], v252 offset:57856
	ds_read_b64_tr_b16 v[150:151], v252 offset:59904
	v_add_f32_e32 v182, v103, v182
	v_exp_f32_e32 v104, v104
	v_exp_f32_e32 v105, v105
	v_exp_f32_e32 v106, v106
	v_mfma_f32_32x32x16_bf16 v[80:95], v[208:211], v[164:167], v[80:95]
	v_exp_f32_e32 v107, v107
	v_add_f32_e32 v182, v104, v182
	v_add_f32_e32 v182, v105, v182
	v_cvt_pk_bf16_f32 v140, v104, v105
	s_waitcnt lgkmcnt(6)
	v_mfma_f32_32x32x16_bf16 v[16:31], v[132:135], v[152:155], v[16:31]
	ds_read_b64_tr_b16 v[152:153], v252 offset:58368
	ds_read_b64_tr_b16 v[154:155], v252 offset:60416
	v_exp_f32_e32 v108, v108
	v_exp_f32_e32 v109, v109
	v_add_f32_e32 v182, v106, v182
	v_add_f32_e32 v182, v107, v182
	v_mfma_f32_32x32x16_bf16 v[64:79], v[212:215], v[164:167], v[64:79]
	v_cvt_pk_bf16_f32 v141, v106, v107
	v_exp_f32_e32 v110, v110
	v_exp_f32_e32 v111, v111
	v_add_f32_e32 v182, v108, v182
	s_waitcnt lgkmcnt(6)
; template <int KS> __device__ __forceinline__ void pv_ks(f32x16* o, int vb, bf16x8 pa) {
;     const s16x4 l0 = tr_read<v_rd_off(0, KS, 0)>(vb), h0 = tr_read<v_rd_off(0, KS, 1)>(vb), l1 = tr_read<v_rd_off(1, KS, 0)>(vb), h1 = tr_read<v_rd_off(1, KS, 1)>(vb);
;     const s16x4 l2 = tr_read<v_rd_off(2, KS, 0)>(vb), h2 = tr_read<v_rd_off(2, KS, 1)>(vb), l3 = tr_read<v_rd_off(3, KS, 0)>(vb), h3 = tr_read<v_rd_off(3, KS, 1)>(vb);
;     ...
;     asm volatile("s_waitcnt lgkmcnt(6)" ::: "memory"); SBAR();
;     o[0] = __builtin_amdgcn_mfma_f32_32x32x16_bf16(pa, PK(l0, h0), o[0], 0, 0, 0);
;     asm volatile("s_waitcnt lgkmcnt(4)" ::: "memory"); SBAR();
;     o[1] = __builtin_amdgcn_mfma_f32_32x32x16_bf16(pa, PK(l1, h1), o[1], 0, 0, 0);
;     asm volatile("s_waitcnt lgkmcnt(2)" ::: "memory"); SBAR();
;     o[2] = __builtin_amdgcn_mfma_f32_32x32x16_bf16(pa, PK(l2, h2), o[2], 0, 0, 0);
;     asm volatile("s_waitcnt lgkmcnt(0)" ::: "memory"); SBAR();
;     o[3] = __builtin_amdgcn_mfma_f32_32x32x16_bf16(pa, PK(l3, h3), o[3], 0, 0, 0);
;     ...
; }
; __device__ __forceinline__ void pv_d0(f32x16* o, int vb, bf16x8 pa0, bf16x8 pa1, bf16x8 pa2, bf16x8 pa3) {
;     __builtin_amdgcn_s_setprio(1);
;     pv_ks<0>(o, vb, pa0); pv_ks<1>(o, vb, pa1); pv_ks<2>(o, vb, pa2); pv_ks<3>(o, vb, pa3);
;     __builtin_amdgcn_s_setprio(0);
; }
; __device__ __forceinline__ void exp_half(f32x16& p) {
; #pragma unroll
;     for (int r = 0; r < 16; ++r) p[r] = __builtin_amdgcn_exp2f(p[r]);
; }
; __device__ __forceinline__ void pack_p(const f32x16& p0, const f32x16& p1, float& l_reg, bf16x8& pa0, bf16x8& pa1, bf16x8& pa2, bf16x8& pa3) {
;     float ps = 0;
; #pragma unroll
;     for (int r = 0; r < 16; ++r) ps += p0[r];
; #pragma unroll
;     for (int r = 0; r < 16; ++r) ps += p1[r];
;     l_reg += ps;
;     ...
;     PK4(p0, 0, pa0); PK4(p0, 8, pa1); PK4(p1, 0, pa2); PK4(p1, 8, pa3);
;     ...
; }
; template <int ND0> __device__ __forceinline__ void qkt(f32x16& p0, f32x16& p1, const char* Ks, const bf16x8* qr, int r32, int hi, int colB0) {
; #pragma unroll
;     for (int d0 = 0; d0 < ND0; ++d0) { const int cb = colB0 + (d0 * 16 + hi * 8) * 2;
;         const bf16x8 b0 = *reinterpret_cast<const bf16x8*>(Ks + KSWZ(r32, cb));
;         const bf16x8 b1 = *reinterpret_cast<const bf16x8*>(Ks + KSWZ(32 + r32, cb));
;         p0 = __builtin_amdgcn_mfma_f32_32x32x16_bf16(b0, qr[d0], p0, 0, 0, 0);
	v_mfma_f32_32x32x16_bf16 v[0:15], v[132:135], v[156:159], v[0:15]
	ds_read_b64_tr_b16 v[156:157], v252 offset:58880
	ds_read_b64_tr_b16 v[158:159], v252 offset:60928
	v_add_f32_e32 v182, v109, v182
	v_cvt_pk_bf16_f32 v142, v108, v109
	v_cvt_pk_bf16_f32 v143, v110, v111
	v_add_f32_e32 v182, v110, v182
	v_add_f32_e32 v182, v111, v182
	s_cmp_lt_i32 s55, 0
	s_cselect_b32 s100, -1.0, 1.0
	v_mul_f32_e32 v185, s100, v186
	v_mfma_f32_32x32x16_bf16 v[80:95], v[216:219], v[160:163], v[80:95]
	v_fma_f32 v187, -v185, v183, s16
	v_fmamk_f32 v112, v185, 0x00000000, v187
	v_fmamk_f32 v113, v185, 0x3f800000, v187
	v_fmamk_f32 v114, v185, 0x40000000, v187
	v_fmamk_f32 v115, v185, 0x40400000, v187
	v_fmamk_f32 v116, v185, 0x41000000, v187
	v_mfma_f32_32x32x16_bf16 v[64:79], v[220:223], v[160:163], v[64:79]
	v_fmamk_f32 v117, v185, 0x41100000, v187
	v_fmamk_f32 v118, v185, 0x41200000, v187
	v_fmamk_f32 v119, v185, 0x41300000, v187
	v_fmamk_f32 v120, v185, 0x41800000, v187
	v_fmamk_f32 v121, v185, 0x41880000, v187
	v_fmamk_f32 v122, v185, 0x41900000, v187
	s_waitcnt lgkmcnt(6)
	v_mfma_f32_32x32x16_bf16 v[48:63], v[136:139], v[144:147], v[48:63]
	ds_read_b64_tr_b16 v[144:145], v252 offset:61440
	ds_read_b64_tr_b16 v[146:147], v252 offset:63488
	v_fmamk_f32 v123, v185, 0x41980000, v187
	v_fmamk_f32 v124, v185, 0x41c00000, v187
	v_fmamk_f32 v125, v185, 0x41c80000, v187
	v_fmamk_f32 v126, v185, 0x41d00000, v187
	v_fmamk_f32 v127, v185, 0x41d80000, v187
	v_fmamk_f32 v96, v185, 0x42000000, v187
	s_waitcnt lgkmcnt(6)
	v_mfma_f32_32x32x16_bf16 v[32:47], v[136:139], v[148:151], v[32:47]
	ds_read_b64_tr_b16 v[148:149], v252 offset:61952
	ds_read_b64_tr_b16 v[150:151], v252 offset:64000
	v_fmamk_f32 v97, v185, 0x42040000, v187
	v_fmamk_f32 v98, v185, 0x42080000, v187
	v_fmamk_f32 v99, v185, 0x420c0000, v187
	v_fmamk_f32 v100, v185, 0x42200000, v187
	v_fmamk_f32 v101, v185, 0x42240000, v187
	v_fmamk_f32 v102, v185, 0x42280000, v187
	s_waitcnt lgkmcnt(6)
	v_mfma_f32_32x32x16_bf16 v[16:31], v[136:139], v[152:155], v[16:31]
	ds_read_b64_tr_b16 v[152:153], v252 offset:62464
	ds_read_b64_tr_b16 v[154:155], v252 offset:64512
	v_fmamk_f32 v103, v185, 0x422c0000, v187
	v_fmamk_f32 v104, v185, 0x42400000, v187
	v_fmamk_f32 v105, v185, 0x42440000, v187
	v_fmamk_f32 v106, v185, 0x42480000, v187
	v_fmamk_f32 v107, v185, 0x424c0000, v187
	v_fmamk_f32 v108, v185, 0x42600000, v187
	s_waitcnt lgkmcnt(6)
	v_mfma_f32_32x32x16_bf16 v[0:15], v[136:139], v[156:159], v[0:15]
	ds_read_b64_tr_b16 v[156:157], v252 offset:62976
	ds_read_b64_tr_b16 v[158:159], v252 offset:65024
	v_fmamk_f32 v109, v185, 0x42640000, v187
	v_fmamk_f32 v110, v185, 0x42680000, v187
	v_fmamk_f32 v111, v185, 0x426c0000, v187
	v_exp_f32_e32 v80, v80
	v_exp_f32_e32 v81, v81
	s_waitcnt lgkmcnt(6)
	v_mfma_f32_32x32x16_bf16 v[48:63], v[140:143], v[144:147], v[48:63]
	ds_read_b64_tr_b16 v[144:145], v252 offset:0
	ds_read_b64_tr_b16 v[146:147], v252 offset:2048
	v_exp_f32_e32 v82, v82
	v_exp_f32_e32 v83, v83
	v_add_f32_e32 v182, v80, v182
	v_add_f32_e32 v182, v81, v182
	s_waitcnt lgkmcnt(6)
	v_mfma_f32_32x32x16_bf16 v[32:47], v[140:143], v[148:151], v[32:47]
	ds_read_b64_tr_b16 v[148:149], v252 offset:512
	ds_read_b64_tr_b16 v[150:151], v252 offset:2560
	v_cvt_pk_bf16_f32 v128, v80, v81
	v_exp_f32_e32 v84, v84
	v_exp_f32_e32 v85, v85
	v_add_f32_e32 v182, v82, v182
	s_waitcnt lgkmcnt(6)
	v_mfma_f32_32x32x16_bf16 v[16:31], v[140:143], v[152:155], v[16:31]
	ds_read_b64_tr_b16 v[152:153], v252 offset:1024
	ds_read_b64_tr_b16 v[154:155], v252 offset:3072
	v_add_f32_e32 v182, v83, v182
	v_cvt_pk_bf16_f32 v129, v82, v83
	v_exp_f32_e32 v86, v86
	v_exp_f32_e32 v87, v87
	s_waitcnt lgkmcnt(6)
	v_mfma_f32_32x32x16_bf16 v[0:15], v[140:143], v[156:159], v[0:15]
	ds_read_b64_tr_b16 v[156:157], v252 offset:1536
	ds_read_b64_tr_b16 v[158:159], v252 offset:3584
	v_add_f32_e32 v182, v84, v182
	v_add_f32_e32 v182, v85, v182
	v_cvt_pk_bf16_f32 v130, v84, v85
	v_cvt_pk_bf16_f32 v131, v86, v87
	v_add_f32_e32 v182, v86, v182
	v_add_f32_e32 v182, v87, v182
	s_add_i32 s100, s55, 62
	s_cmp_lt_u32 s100, 93
	s_cbranch_scc1 .Lsym_diagblk_s3

; __device__ __forceinline__ void bias_init(f32x16& p0, f32x16& p1, float base, float nslope2, float nM2, int rel  ) {
;     if (rel <= -63 || rel >= 31) {
;         const float sg = (rel < 0) ? -nslope2 : nslope2, lbv = fmaf(-sg, base, nM2);
; #pragma unroll
;         for (int r = 0; r < 16; ++r) { p0[r] = fmaf((float)((r & 3) + 8 * (r >> 2)), sg, lbv); p1[r] = fmaf((float)((r & 3) + 8 * (r >> 2) + 32), sg, lbv); }
;     } else {
; #pragma unroll
;         for (int r = 0; r < 16; ++r) { const float d = base - (float)((r & 3) + 8 * (r >> 2));
;             p0[r] = fmaf(fabsf(d), nslope2, nM2); p1[r] = fmaf(fabsf(d - 32.f), nslope2, nM2); }
;     }
.Lsym_diagblk_s0:
	v_add_f32_e32 v190, 0x00000000, v183
	v_add_f32_e32 v191, 0xc2000000, v183
	v_fma_f32 v80, |v190|, v186, s16
	v_fma_f32 v64, |v191|, v186, s16
	v_add_f32_e32 v190, 0xbf800000, v183
	v_add_f32_e32 v191, 0xc2040000, v183
	v_fma_f32 v81, |v190|, v186, s16
	v_fma_f32 v65, |v191|, v186, s16
	v_add_f32_e32 v190, 0xc0000000, v183
	v_add_f32_e32 v191, 0xc2080000, v183
	v_fma_f32 v82, |v190|, v186, s16
	v_fma_f32 v66, |v191|, v186, s16
	v_add_f32_e32 v190, 0xc0400000, v183
	v_add_f32_e32 v191, 0xc20c0000, v183
	v_fma_f32 v83, |v190|, v186, s16
	v_fma_f32 v67, |v191|, v186, s16
	v_add_f32_e32 v190, 0xc1000000, v183
	v_add_f32_e32 v191, 0xc2200000, v183
	v_fma_f32 v84, |v190|, v186, s16
	v_fma_f32 v68, |v191|, v186, s16
	v_add_f32_e32 v190, 0xc1100000, v183
	v_add_f32_e32 v191, 0xc2240000, v183
	v_fma_f32 v85, |v190|, v186, s16
	v_fma_f32 v69, |v191|, v186, s16
	v_add_f32_e32 v190, 0xc1200000, v183
	v_add_f32_e32 v191, 0xc2280000, v183
	v_fma_f32 v86, |v190|, v186, s16
	v_fma_f32 v70, |v191|, v186, s16
	v_add_f32_e32 v190, 0xc1300000, v183
	v_add_f32_e32 v191, 0xc22c0000, v183
	v_fma_f32 v87, |v190|, v186, s16
	v_fma_f32 v71, |v191|, v186, s16
	v_add_f32_e32 v190, 0xc1800000, v183
	v_add_f32_e32 v191, 0xc2400000, v183
	v_fma_f32 v88, |v190|, v186, s16
	v_fma_f32 v72, |v191|, v186, s16
	v_add_f32_e32 v190, 0xc1880000, v183
	v_add_f32_e32 v191, 0xc2440000, v183
	v_fma_f32 v89, |v190|, v186, s16
	v_fma_f32 v73, |v191|, v186, s16
	v_add_f32_e32 v190, 0xc1900000, v183
	v_add_f32_e32 v191, 0xc2480000, v183
	v_fma_f32 v90, |v190|, v186, s16
	v_fma_f32 v74, |v191|, v186, s16
	v_add_f32_e32 v190, 0xc1980000, v183
	v_add_f32_e32 v191, 0xc24c0000, v183
	v_fma_f32 v91, |v190|, v186, s16
	v_fma_f32 v75, |v191|, v186, s16
	v_add_f32_e32 v190, 0xc1c00000, v183
	v_add_f32_e32 v191, 0xc2600000, v183
	v_fma_f32 v92, |v190|, v186, s16
	v_fma_f32 v76, |v191|, v186, s16
	v_add_f32_e32 v190, 0xc1c80000, v183
	v_add_f32_e32 v191, 0xc2640000, v183
	v_fma_f32 v93, |v190|, v186, s16
	v_fma_f32 v77, |v191|, v186, s16
	v_add_f32_e32 v190, 0xc1d00000, v183
	v_add_f32_e32 v191, 0xc2680000, v183
	v_fma_f32 v94, |v190|, v186, s16
	v_fma_f32 v78, |v191|, v186, s16
	v_add_f32_e32 v190, 0xc1d80000, v183
	v_add_f32_e32 v191, 0xc26c0000, v183
	v_fma_f32 v95, |v190|, v186, s16
	v_fma_f32 v79, |v191|, v186, s16
	s_branch .Lsym_nodiag_s0
.Lsym_diagblk_s1:
	v_add_f32_e32 v190, 0x00000000, v183
	v_add_f32_e32 v191, 0xc2000000, v183
	v_fma_f32 v112, |v190|, v186, s16
	v_fma_f32 v96, |v191|, v186, s16
	v_add_f32_e32 v190, 0xbf800000, v183
	v_add_f32_e32 v191, 0xc2040000, v183
	v_fma_f32 v113, |v190|, v186, s16
	v_fma_f32 v97, |v191|, v186, s16
	v_add_f32_e32 v190, 0xc0000000, v183
	v_add_f32_e32 v191, 0xc2080000, v183
	v_fma_f32 v114, |v190|, v186, s16
	v_fma_f32 v98, |v191|, v186, s16
	v_add_f32_e32 v190, 0xc0400000, v183
	v_add_f32_e32 v191, 0xc20c0000, v183
	v_fma_f32 v115, |v190|, v186, s16
	v_fma_f32 v99, |v191|, v186, s16
	v_add_f32_e32 v190, 0xc1000000, v183
	v_add_f32_e32 v191, 0xc2200000, v183
	v_fma_f32 v116, |v190|, v186, s16
	v_fma_f32 v100, |v191|, v186, s16
	v_add_f32_e32 v190, 0xc1100000, v183
	v_add_f32_e32 v191, 0xc2240000, v183
	v_fma_f32 v117, |v190|, v186, s16
	v_fma_f32 v101, |v191|, v186, s16
	v_add_f32_e32 v190, 0xc1200000, v183
	v_add_f32_e32 v191, 0xc2280000, v183
	v_fma_f32 v118, |v190|, v186, s16
	v_fma_f32 v102, |v191|, v186, s16
	v_add_f32_e32 v190, 0xc1300000, v183
	v_add_f32_e32 v191, 0xc22c0000, v183
	v_fma_f32 v119, |v190|, v186, s16
	v_fma_f32 v103, |v191|, v186, s16
	v_add_f32_e32 v190, 0xc1800000, v183
	v_add_f32_e32 v191, 0xc2400000, v183
	v_fma_f32 v120, |v190|, v186, s16
	v_fma_f32 v104, |v191|, v186, s16
	v_add_f32_e32 v190, 0xc1880000, v183
	v_add_f32_e32 v191, 0xc2440000, v183
	v_fma_f32 v121, |v190|, v186, s16
	v_fma_f32 v105, |v191|, v186, s16
	v_add_f32_e32 v190, 0xc1900000, v183
	v_add_f32_e32 v191, 0xc2480000, v183
	v_fma_f32 v122, |v190|, v186, s16
	v_fma_f32 v106, |v191|, v186, s16
	v_add_f32_e32 v190, 0xc1980000, v183
	v_add_f32_e32 v191, 0xc24c0000, v183
	v_fma_f32 v123, |v190|, v186, s16
	v_fma_f32 v107, |v191|, v186, s16
	v_add_f32_e32 v190, 0xc1c00000, v183
	v_add_f32_e32 v191, 0xc2600000, v183
	v_fma_f32 v124, |v190|, v186, s16
	v_fma_f32 v108, |v191|, v186, s16
	v_add_f32_e32 v190, 0xc1c80000, v183
	v_add_f32_e32 v191, 0xc2640000, v183
	v_fma_f32 v125, |v190|, v186, s16
	v_fma_f32 v109, |v191|, v186, s16
	v_add_f32_e32 v190, 0xc1d00000, v183
	v_add_f32_e32 v191, 0xc2680000, v183
	v_fma_f32 v126, |v190|, v186, s16
	v_fma_f32 v110, |v191|, v186, s16
	v_add_f32_e32 v190, 0xc1d80000, v183
	v_add_f32_e32 v191, 0xc26c0000, v183
	v_fma_f32 v127, |v190|, v186, s16
	v_fma_f32 v111, |v191|, v186, s16
	s_branch .Lsym_nodiag_s1
